# P0b+P6+P10 rmsnorm-style row phases hand-rescheduled: gains hoisted, whole-row loads, row prefetch, no store drains
# speedup vs baseline: 1.0244x; 1.0087x over previous
.LBB0_77:
	s_lshl_b32 s2, s47, 3
	s_mov_b32 s0, s2
	s_waitcnt vmcnt(0)
	v_lshrrev_b32_e32 v9, 6, v49
	v_writelane_b32 v252, s0, 40
	s_lshl_b32 s50, s46, 3
	v_writelane_b32 v252, s1, 41
	v_mbcnt_lo_u32_b32 v209, -1, 0
	v_and_b32_e32 v10, 63, v49
	v_readlane_b32 s16, v252, 14
	v_readlane_b32 s17, v252, 15
	v_readlane_b32 s18, v252, 18
	v_readlane_b32 s19, v252, 19
	v_readfirstlane_b32 s3, v9
	v_lshlrev_b32_e32 v0, 4, v10
	v_lshlrev_b32_e32 v1, 3, v10
	v_add_u32_e32 v124, 0x1000, v0
	v_lshlrev_b32_e32 v11, 2, v10
	v_xor_b32_e32 v2, 0x80, v11
	v_xor_b32_e32 v3, 64, v11
	v_xor_b32_e32 v4, 32, v11
	v_xor_b32_e32 v5, 16, v11
	v_xor_b32_e32 v6, 8, v11
	v_xor_b32_e32 v7, 4, v11
	v_mov_b32_e32 v8, 0x358637bd
	v_mov_b32_e32 v122, 0
	v_mov_b32_e32 v123, 0
	s_add_i32 s2, s2, s3
	s_mov_b32 s3, s50
	s_mov_b32 s10, 0
	s_mov_b64 s[76:77], s[16:17]
	s_waitcnt lgkmcnt(0)
	global_load_dwordx4 v[12:15], v0, s[76:77]
	global_load_dwordx4 v[16:19], v0, s[76:77] offset:1024
	global_load_dwordx4 v[20:23], v0, s[76:77] offset:2048
	global_load_dwordx4 v[24:27], v0, s[76:77] offset:3072
	global_load_dwordx4 v[28:31], v124, s[76:77]
	global_load_dwordx4 v[32:35], v124, s[76:77] offset:1024
	global_load_dwordx4 v[36:39], v124, s[76:77] offset:2048
	global_load_dwordx4 v[40:43], v124, s[76:77] offset:3072
.Lp0b_restart:
	s_cmp_ge_u32 s2, 0x2300
	s_cbranch_scc1 .Lp0b_done
	s_cmp_lt_u32 s2, 0x2080
	s_cbranch_scc1 .Lp0b_ld
	s_cmp_ge_u32 s2, 0x2100
	s_cbranch_scc1 .Lp0b_ld
	s_lshl_b32 s4, s2, 12
	s_add_u32 s8, s96, s4
	s_addc_u32 s9, s97, 0
	global_store_dwordx2 v1, v[122:123], s[8:9]
	global_store_dwordx2 v1, v[122:123], s[8:9] offset:512
	global_store_dwordx2 v1, v[122:123], s[8:9] offset:1024
	global_store_dwordx2 v1, v[122:123], s[8:9] offset:1536
	global_store_dwordx2 v1, v[122:123], s[8:9] offset:2048
	global_store_dwordx2 v1, v[122:123], s[8:9] offset:2560
	global_store_dwordx2 v1, v[122:123], s[8:9] offset:3072
	global_store_dwordx2 v1, v[122:123], s[8:9] offset:3584
	s_add_u32 s2, s2, s3
	s_branch .Lp0b_restart
.Lp0b_ld:
	s_sub_u32 s4, s2, 0x2100
	s_and_b32 s4, s4, 0xff
	s_sub_u32 s5, s2, 0x2000
	s_cmp_lt_u32 s2, 0x2080
	s_cselect_b32 s4, s5, s4
	s_cselect_b32 s6, s62, s74
	s_cselect_b32 s7, s63, s75
	s_cmp_lt_u32 s2, 0x2000
	s_cselect_b32 s4, s2, s4
	s_cselect_b32 s6, s60, s6
	s_cselect_b32 s7, s61, s7
	s_lshl_b32 s4, s4, 13
	s_add_u32 s6, s6, s4
	s_addc_u32 s7, s7, 0
	global_load_dwordx4 v[52:55], v0, s[6:7]
	global_load_dwordx4 v[56:59], v0, s[6:7] offset:1024
	global_load_dwordx4 v[60:63], v0, s[6:7] offset:2048
	global_load_dwordx4 v[64:67], v0, s[6:7] offset:3072
	global_load_dwordx4 v[68:71], v124, s[6:7]
	global_load_dwordx4 v[72:75], v124, s[6:7] offset:1024
	global_load_dwordx4 v[76:79], v124, s[6:7] offset:2048
	global_load_dwordx4 v[80:83], v124, s[6:7] offset:3072
	s_waitcnt vmcnt(0)
	s_branch .Lp0b_A_go
.Lp0b_A:
	s_waitcnt vmcnt(8)
.Lp0b_A_go:
	s_add_u32 s12, s2, s3
	s_cmp_lt_u32 s12, 0x2080
	s_cbranch_scc1 .Lp0b_A_pf
	s_cmp_lt_u32 s12, 0x2100
	s_cbranch_scc1 .Lp0b_A_nopf
	s_cmp_ge_u32 s12, 0x2300
	s_cbranch_scc1 .Lp0b_A_nopf
.Lp0b_A_pf:
	s_sub_u32 s4, s12, 0x2100
	s_and_b32 s4, s4, 0xff
	s_sub_u32 s5, s12, 0x2000
	s_cmp_lt_u32 s12, 0x2080
	s_cselect_b32 s4, s5, s4
	s_cselect_b32 s6, s62, s74
	s_cselect_b32 s7, s63, s75
	s_cmp_lt_u32 s12, 0x2000
	s_cselect_b32 s4, s12, s4
	s_cselect_b32 s6, s60, s6
	s_cselect_b32 s7, s61, s7
	s_lshl_b32 s4, s4, 13
	s_add_u32 s6, s6, s4
	s_addc_u32 s7, s7, 0
	global_load_dwordx4 v[84:87], v0, s[6:7]
	global_load_dwordx4 v[88:91], v0, s[6:7] offset:1024
	global_load_dwordx4 v[92:95], v0, s[6:7] offset:2048
	global_load_dwordx4 v[96:99], v0, s[6:7] offset:3072
	global_load_dwordx4 v[100:103], v124, s[6:7]
	global_load_dwordx4 v[104:107], v124, s[6:7] offset:1024
	global_load_dwordx4 v[108:111], v124, s[6:7] offset:2048
	global_load_dwordx4 v[112:115], v124, s[6:7] offset:3072
	s_mov_b32 s11, 1
	s_branch .Lp0b_A_gc
.Lp0b_A_nopf:
	s_mov_b32 s11, 0
.Lp0b_A_gc:
	s_sub_u32 s4, s2, 0x2100
	s_lshr_b32 s4, s4, 8
	s_add_u32 s4, s4, 1
	s_cmp_lt_u32 s2, 0x2100
	s_cselect_b32 s4, 0, s4
	s_cmp_eq_u32 s4, s10
	s_cbranch_scc1 .Lp0b_A_gok
	s_mov_b32 s10, s4
	s_sub_u32 s5, s4, 1
	s_lshl_b32 s5, s5, 13
	s_add_u32 s76, s18, s5
	s_addc_u32 s77, s19, 0
	s_cmp_eq_u32 s4, 0
	s_cselect_b32 s76, s16, s76
	s_cselect_b32 s77, s17, s77
	global_load_dwordx4 v[12:15], v0, s[76:77]
	global_load_dwordx4 v[16:19], v0, s[76:77] offset:1024
	global_load_dwordx4 v[20:23], v0, s[76:77] offset:2048
	global_load_dwordx4 v[24:27], v0, s[76:77] offset:3072
	global_load_dwordx4 v[28:31], v124, s[76:77]
	global_load_dwordx4 v[32:35], v124, s[76:77] offset:1024
	global_load_dwordx4 v[36:39], v124, s[76:77] offset:2048
	global_load_dwordx4 v[40:43], v124, s[76:77] offset:3072
	s_waitcnt vmcnt(0)
.Lp0b_A_gok:
	s_lshl_b32 s4, s2, 12
	s_add_u32 s8, s96, s4
	s_addc_u32 s9, s97, 0
	v_mul_f32_e32 v116, v52, v52
	v_mul_f32_e32 v117, v53, v53
	v_mul_f32_e32 v118, v54, v54
	v_mul_f32_e32 v119, v55, v55
	v_fmac_f32_e32 v116, v56, v56
	v_fmac_f32_e32 v117, v57, v57
	v_fmac_f32_e32 v118, v58, v58
	v_fmac_f32_e32 v119, v59, v59
	v_fmac_f32_e32 v116, v60, v60
	v_fmac_f32_e32 v117, v61, v61
	v_fmac_f32_e32 v118, v62, v62
	v_fmac_f32_e32 v119, v63, v63
	v_fmac_f32_e32 v116, v64, v64
	v_fmac_f32_e32 v117, v65, v65
	v_fmac_f32_e32 v118, v66, v66
	v_fmac_f32_e32 v119, v67, v67
	v_fmac_f32_e32 v116, v68, v68
	v_fmac_f32_e32 v117, v69, v69
	v_fmac_f32_e32 v118, v70, v70
	v_fmac_f32_e32 v119, v71, v71
	v_fmac_f32_e32 v116, v72, v72
	v_fmac_f32_e32 v117, v73, v73
	v_fmac_f32_e32 v118, v74, v74
	v_fmac_f32_e32 v119, v75, v75
	v_fmac_f32_e32 v116, v76, v76
	v_fmac_f32_e32 v117, v77, v77
	v_fmac_f32_e32 v118, v78, v78
	v_fmac_f32_e32 v119, v79, v79
	v_fmac_f32_e32 v116, v80, v80
	v_fmac_f32_e32 v117, v81, v81
	v_fmac_f32_e32 v118, v82, v82
	v_fmac_f32_e32 v119, v83, v83
	v_add_f32_e32 v116, v116, v117
	v_add_f32_e32 v118, v118, v119
	v_add_f32_e32 v116, v116, v118
	ds_bpermute_b32 v120, v2, v116
	s_waitcnt lgkmcnt(0)
	v_add_f32_e32 v116, v116, v120
	ds_bpermute_b32 v120, v3, v116
	s_waitcnt lgkmcnt(0)
	v_add_f32_e32 v116, v116, v120
	ds_bpermute_b32 v120, v4, v116
	s_waitcnt lgkmcnt(0)
	v_add_f32_e32 v116, v116, v120
	ds_bpermute_b32 v120, v5, v116
	s_waitcnt lgkmcnt(0)
	v_add_f32_e32 v116, v116, v120
	ds_bpermute_b32 v120, v6, v116
	s_waitcnt lgkmcnt(0)
	v_add_f32_e32 v116, v116, v120
	ds_bpermute_b32 v120, v7, v116
	s_waitcnt lgkmcnt(0)
	v_add_f32_e32 v116, v116, v120
	v_fmamk_f32 v116, v116, 0x3a000000, v8
	v_rsq_f32_e32 v121, v116
	s_nop 0
	v_mul_f32_e32 v52, v52, v121
	v_mul_f32_e32 v52, v52, v12
	v_mul_f32_e32 v53, v53, v121
	v_mul_f32_e32 v53, v53, v13
	v_mul_f32_e32 v54, v54, v121
	v_mul_f32_e32 v54, v54, v14
	v_mul_f32_e32 v55, v55, v121
	v_mul_f32_e32 v55, v55, v15
	v_mul_f32_e32 v56, v56, v121
	v_mul_f32_e32 v56, v56, v16
	v_mul_f32_e32 v57, v57, v121
	v_mul_f32_e32 v57, v57, v17
	v_mul_f32_e32 v58, v58, v121
	v_mul_f32_e32 v58, v58, v18
	v_mul_f32_e32 v59, v59, v121
	v_mul_f32_e32 v59, v59, v19
	v_mul_f32_e32 v60, v60, v121
	v_mul_f32_e32 v60, v60, v20
	v_mul_f32_e32 v61, v61, v121
	v_mul_f32_e32 v61, v61, v21
	v_mul_f32_e32 v62, v62, v121
	v_mul_f32_e32 v62, v62, v22
	v_mul_f32_e32 v63, v63, v121
	v_mul_f32_e32 v63, v63, v23
	v_mul_f32_e32 v64, v64, v121
	v_mul_f32_e32 v64, v64, v24
	v_mul_f32_e32 v65, v65, v121
	v_mul_f32_e32 v65, v65, v25
	v_mul_f32_e32 v66, v66, v121
	v_mul_f32_e32 v66, v66, v26
	v_mul_f32_e32 v67, v67, v121
	v_mul_f32_e32 v67, v67, v27
	v_mul_f32_e32 v68, v68, v121
	v_mul_f32_e32 v68, v68, v28
	v_mul_f32_e32 v69, v69, v121
	v_mul_f32_e32 v69, v69, v29
	v_mul_f32_e32 v70, v70, v121
	v_mul_f32_e32 v70, v70, v30
	v_mul_f32_e32 v71, v71, v121
	v_mul_f32_e32 v71, v71, v31
	v_mul_f32_e32 v72, v72, v121
	v_mul_f32_e32 v72, v72, v32
	v_mul_f32_e32 v73, v73, v121
	v_mul_f32_e32 v73, v73, v33
	v_mul_f32_e32 v74, v74, v121
	v_mul_f32_e32 v74, v74, v34
	v_mul_f32_e32 v75, v75, v121
	v_mul_f32_e32 v75, v75, v35
	v_mul_f32_e32 v76, v76, v121
	v_mul_f32_e32 v76, v76, v36
	v_mul_f32_e32 v77, v77, v121
	v_mul_f32_e32 v77, v77, v37
	v_mul_f32_e32 v78, v78, v121
	v_mul_f32_e32 v78, v78, v38
	v_mul_f32_e32 v79, v79, v121
	v_mul_f32_e32 v79, v79, v39
	v_mul_f32_e32 v80, v80, v121
	v_mul_f32_e32 v80, v80, v40
	v_mul_f32_e32 v81, v81, v121
	v_mul_f32_e32 v81, v81, v41
	v_mul_f32_e32 v82, v82, v121
	v_mul_f32_e32 v82, v82, v42
	v_mul_f32_e32 v83, v83, v121
	v_mul_f32_e32 v83, v83, v43
	v_cvt_pk_bf16_f32 v52, v52, v53
	v_cvt_pk_bf16_f32 v53, v54, v55
	v_cvt_pk_bf16_f32 v56, v56, v57
	v_cvt_pk_bf16_f32 v57, v58, v59
	v_cvt_pk_bf16_f32 v60, v60, v61
	v_cvt_pk_bf16_f32 v61, v62, v63
	v_cvt_pk_bf16_f32 v64, v64, v65
	v_cvt_pk_bf16_f32 v65, v66, v67
	v_cvt_pk_bf16_f32 v68, v68, v69
	v_cvt_pk_bf16_f32 v69, v70, v71
	v_cvt_pk_bf16_f32 v72, v72, v73
	v_cvt_pk_bf16_f32 v73, v74, v75
	v_cvt_pk_bf16_f32 v76, v76, v77
	v_cvt_pk_bf16_f32 v77, v78, v79
	v_cvt_pk_bf16_f32 v80, v80, v81
	v_cvt_pk_bf16_f32 v81, v82, v83
	global_store_dwordx2 v1, v[52:53], s[8:9]
	global_store_dwordx2 v1, v[56:57], s[8:9] offset:512
	global_store_dwordx2 v1, v[60:61], s[8:9] offset:1024
	global_store_dwordx2 v1, v[64:65], s[8:9] offset:1536
	global_store_dwordx2 v1, v[68:69], s[8:9] offset:2048
	global_store_dwordx2 v1, v[72:73], s[8:9] offset:2560
	global_store_dwordx2 v1, v[76:77], s[8:9] offset:3072
	global_store_dwordx2 v1, v[80:81], s[8:9] offset:3584
	s_mov_b32 s2, s12
	s_cmp_eq_u32 s11, 0
	s_cbranch_scc1 .Lp0b_restart

.Lp0b_B_pf:
	s_sub_u32 s4, s12, 0x2100
	s_and_b32 s4, s4, 0xff
	s_sub_u32 s5, s12, 0x2000
	s_cmp_lt_u32 s12, 0x2080
	s_cselect_b32 s4, s5, s4
	s_cselect_b32 s6, s62, s74
	s_cselect_b32 s7, s63, s75
	s_cmp_lt_u32 s12, 0x2000
	s_cselect_b32 s4, s12, s4
	s_cselect_b32 s6, s60, s6
	s_cselect_b32 s7, s61, s7
	s_lshl_b32 s4, s4, 13
	s_add_u32 s6, s6, s4
	s_addc_u32 s7, s7, 0
	global_load_dwordx4 v[52:55], v0, s[6:7]
	global_load_dwordx4 v[56:59], v0, s[6:7] offset:1024
	global_load_dwordx4 v[60:63], v0, s[6:7] offset:2048
	global_load_dwordx4 v[64:67], v0, s[6:7] offset:3072
	global_load_dwordx4 v[68:71], v124, s[6:7]
	global_load_dwordx4 v[72:75], v124, s[6:7] offset:1024
	global_load_dwordx4 v[76:79], v124, s[6:7] offset:2048
	global_load_dwordx4 v[80:83], v124, s[6:7] offset:3072
	s_mov_b32 s11, 1
	s_branch .Lp0b_B_gc

.Lp0b_B_gok:
	s_lshl_b32 s4, s2, 12
	s_add_u32 s8, s96, s4
	s_addc_u32 s9, s97, 0
	v_mul_f32_e32 v116, v84, v84
	v_mul_f32_e32 v117, v85, v85
	v_mul_f32_e32 v118, v86, v86
	v_mul_f32_e32 v119, v87, v87
	v_fmac_f32_e32 v116, v88, v88
	v_fmac_f32_e32 v117, v89, v89
	v_fmac_f32_e32 v118, v90, v90
	v_fmac_f32_e32 v119, v91, v91
	v_fmac_f32_e32 v116, v92, v92
	v_fmac_f32_e32 v117, v93, v93
	v_fmac_f32_e32 v118, v94, v94
	v_fmac_f32_e32 v119, v95, v95
	v_fmac_f32_e32 v116, v96, v96
	v_fmac_f32_e32 v117, v97, v97
	v_fmac_f32_e32 v118, v98, v98
	v_fmac_f32_e32 v119, v99, v99
	v_fmac_f32_e32 v116, v100, v100
	v_fmac_f32_e32 v117, v101, v101
	v_fmac_f32_e32 v118, v102, v102
	v_fmac_f32_e32 v119, v103, v103
	v_fmac_f32_e32 v116, v104, v104
	v_fmac_f32_e32 v117, v105, v105
	v_fmac_f32_e32 v118, v106, v106
	v_fmac_f32_e32 v119, v107, v107
	v_fmac_f32_e32 v116, v108, v108
	v_fmac_f32_e32 v117, v109, v109
	v_fmac_f32_e32 v118, v110, v110
	v_fmac_f32_e32 v119, v111, v111
	v_fmac_f32_e32 v116, v112, v112
	v_fmac_f32_e32 v117, v113, v113
	v_fmac_f32_e32 v118, v114, v114
	v_fmac_f32_e32 v119, v115, v115
	v_add_f32_e32 v116, v116, v117
	v_add_f32_e32 v118, v118, v119
	v_add_f32_e32 v116, v116, v118
	ds_bpermute_b32 v120, v2, v116
	s_waitcnt lgkmcnt(0)
	v_add_f32_e32 v116, v116, v120
	ds_bpermute_b32 v120, v3, v116
	s_waitcnt lgkmcnt(0)
	v_add_f32_e32 v116, v116, v120
	ds_bpermute_b32 v120, v4, v116
	s_waitcnt lgkmcnt(0)
	v_add_f32_e32 v116, v116, v120
	ds_bpermute_b32 v120, v5, v116
	s_waitcnt lgkmcnt(0)
	v_add_f32_e32 v116, v116, v120
	ds_bpermute_b32 v120, v6, v116
	s_waitcnt lgkmcnt(0)
	v_add_f32_e32 v116, v116, v120
	ds_bpermute_b32 v120, v7, v116
	s_waitcnt lgkmcnt(0)
	v_add_f32_e32 v116, v116, v120
	v_fmamk_f32 v116, v116, 0x3a000000, v8
	v_rsq_f32_e32 v121, v116
	s_nop 0
	v_mul_f32_e32 v84, v84, v121
	v_mul_f32_e32 v84, v84, v12
	v_mul_f32_e32 v85, v85, v121
	v_mul_f32_e32 v85, v85, v13
	v_mul_f32_e32 v86, v86, v121
	v_mul_f32_e32 v86, v86, v14
	v_mul_f32_e32 v87, v87, v121
	v_mul_f32_e32 v87, v87, v15
	v_mul_f32_e32 v88, v88, v121
	v_mul_f32_e32 v88, v88, v16
	v_mul_f32_e32 v89, v89, v121
	v_mul_f32_e32 v89, v89, v17
	v_mul_f32_e32 v90, v90, v121
	v_mul_f32_e32 v90, v90, v18
	v_mul_f32_e32 v91, v91, v121
	v_mul_f32_e32 v91, v91, v19
	v_mul_f32_e32 v92, v92, v121
	v_mul_f32_e32 v92, v92, v20
	v_mul_f32_e32 v93, v93, v121
	v_mul_f32_e32 v93, v93, v21
	v_mul_f32_e32 v94, v94, v121
	v_mul_f32_e32 v94, v94, v22
	v_mul_f32_e32 v95, v95, v121
	v_mul_f32_e32 v95, v95, v23
	v_mul_f32_e32 v96, v96, v121
	v_mul_f32_e32 v96, v96, v24
	v_mul_f32_e32 v97, v97, v121
	v_mul_f32_e32 v97, v97, v25
	v_mul_f32_e32 v98, v98, v121
	v_mul_f32_e32 v98, v98, v26
	v_mul_f32_e32 v99, v99, v121
	v_mul_f32_e32 v99, v99, v27
	v_mul_f32_e32 v100, v100, v121
	v_mul_f32_e32 v100, v100, v28
	v_mul_f32_e32 v101, v101, v121
	v_mul_f32_e32 v101, v101, v29
	v_mul_f32_e32 v102, v102, v121
	v_mul_f32_e32 v102, v102, v30
	v_mul_f32_e32 v103, v103, v121
	v_mul_f32_e32 v103, v103, v31
	v_mul_f32_e32 v104, v104, v121
	v_mul_f32_e32 v104, v104, v32
	v_mul_f32_e32 v105, v105, v121
	v_mul_f32_e32 v105, v105, v33
	v_mul_f32_e32 v106, v106, v121
	v_mul_f32_e32 v106, v106, v34
	v_mul_f32_e32 v107, v107, v121
	v_mul_f32_e32 v107, v107, v35
	v_mul_f32_e32 v108, v108, v121
	v_mul_f32_e32 v108, v108, v36
	v_mul_f32_e32 v109, v109, v121
	v_mul_f32_e32 v109, v109, v37
	v_mul_f32_e32 v110, v110, v121
	v_mul_f32_e32 v110, v110, v38
	v_mul_f32_e32 v111, v111, v121
	v_mul_f32_e32 v111, v111, v39
	v_mul_f32_e32 v112, v112, v121
	v_mul_f32_e32 v112, v112, v40
	v_mul_f32_e32 v113, v113, v121
	v_mul_f32_e32 v113, v113, v41
	v_mul_f32_e32 v114, v114, v121
	v_mul_f32_e32 v114, v114, v42
	v_mul_f32_e32 v115, v115, v121
	v_mul_f32_e32 v115, v115, v43
	v_cvt_pk_bf16_f32 v84, v84, v85
	v_cvt_pk_bf16_f32 v85, v86, v87
	v_cvt_pk_bf16_f32 v88, v88, v89
	v_cvt_pk_bf16_f32 v89, v90, v91
	v_cvt_pk_bf16_f32 v92, v92, v93
	v_cvt_pk_bf16_f32 v93, v94, v95
	v_cvt_pk_bf16_f32 v96, v96, v97
	v_cvt_pk_bf16_f32 v97, v98, v99
	v_cvt_pk_bf16_f32 v100, v100, v101
	v_cvt_pk_bf16_f32 v101, v102, v103
	v_cvt_pk_bf16_f32 v104, v104, v105
	v_cvt_pk_bf16_f32 v105, v106, v107
	v_cvt_pk_bf16_f32 v108, v108, v109
	v_cvt_pk_bf16_f32 v109, v110, v111
	v_cvt_pk_bf16_f32 v112, v112, v113
	v_cvt_pk_bf16_f32 v113, v114, v115
	global_store_dwordx2 v1, v[84:85], s[8:9]
	global_store_dwordx2 v1, v[88:89], s[8:9] offset:512
	global_store_dwordx2 v1, v[92:93], s[8:9] offset:1024
	global_store_dwordx2 v1, v[96:97], s[8:9] offset:1536
	global_store_dwordx2 v1, v[100:101], s[8:9] offset:2048
	global_store_dwordx2 v1, v[104:105], s[8:9] offset:2560
	global_store_dwordx2 v1, v[108:109], s[8:9] offset:3072
	global_store_dwordx2 v1, v[112:113], s[8:9] offset:3584
	s_mov_b32 s2, s12
	s_cmp_eq_u32 s11, 0
	s_cbranch_scc1 .Lp0b_restart
	s_branch .Lp0b_A
.Lp0b_done:
	s_add_u32 s12, s96, 0x30c90800
	s_addc_u32 s13, s97, 0
	s_add_u32 s14, s96, 0x30ea0800
	s_addc_u32 s15, s97, 0
	s_add_u32 s16, s96, 0x310b0800
	s_addc_u32 s17, s97, 0
	s_add_u32 s18, s96, 0x31134800
	s_addc_u32 s19, s97, 0
	s_lshl_b32 s1, s47, 9
	v_writelane_b32 v252, s1, 42
	v_add_u32_e32 v0, s1, v49
	s_mov_b32 s1, 0xa5000
	s_lshl_b32 s0, s46, 9
	v_cmp_gt_i32_e32 vcc, s1, v0
	s_and_saveexec_b64 s[10:11], vcc
	s_cbranch_execz .LBB0_113
	s_mov_b32 s22, 0x31739010
	s_mov_b64 s[20:21], 0
	v_mov_b32_e32 v1, 0x2000
	s_mov_b32 s28, 0x3f2aaaab
	v_mov_b32_e32 v7, 0x3e91f4c4
	s_mov_b32 s1, 0x3f2aaaaa
	s_mov_b32 s23, 0xbf2aaaaa
	s_mov_b32 s29, 0x3f317218
	s_movk_i32 s30, 0x204
	s_mov_b32 s31, 0x7f800000
	s_mov_b32 s33, 0x42b17218
	s_mov_b32 s34, 0x3fb8aa3b
	s_mov_b32 s35, 0xc2ce8ed0
	s_brev_b32 s36, 18
	s_mov_b32 s37, 0xfe5163ab
	v_mov_b32_e32 v3, 0
	s_mov_b32 s38, 0x3c439041
	s_mov_b32 s39, 0xdb629599
	s_mov_b32 s40, 0xf534ddc0
	s_mov_b32 s41, 0xfc2757d1
	s_mov_b32 s42, 0x4e441529
	s_mov_b32 s43, 0xa2f9836e
	s_mov_b32 s44, 0x3fc90fda
	s_mov_b32 s45, 0x3f22f983
	s_mov_b32 s48, 0xbfc90fda
	v_mov_b32_e32 v10, 0x3c0881c4
	v_mov_b32_e32 v11, 0xbab64f3b
	s_brev_b32 s49, 1
	s_movk_i32 s51, 0x1f8
	v_mov_b32_e32 v12, 0x48f42400
	v_mov_b32_e32 v5, 0x3f2aaaaa
	v_mov_b32_e32 v13, 0x37000000
	v_mov_b32_e32 v14, 0x7f800000
	v_not_b32_e32 v15, 63
	v_not_b32_e32 v16, 31
	v_mov_b32_e32 v17, 0x7fc00000
	v_mov_b32_e32 v18, 0x461c4000
	v_mov_b32_e32 v6, v0
	s_branch .LBB0_94

.LBB0_1462:
	s_or_b64 exec, exec, s[0:1]
	s_waitcnt lgkmcnt(0)
	s_barrier
	v_and_b32_e32 v3, 63, v208
	v_lshrrev_b32_e32 v4, 6, v208
	v_readlane_b32 s18, v252, 16
	v_readlane_b32 s19, v252, 17
	v_readlane_b32 s22, v252, 2
	v_readlane_b32 s23, v252, 3
	v_lshlrev_b32_e32 v0, 4, v3
	v_readfirstlane_b32 s2, v4
	v_lshlrev_b32_e32 v1, 5, v3
	v_lshlrev_b32_e32 v4, 2, v3
	v_add_u32_e32 v2, 0x1000, v1
	v_xor_b32_e32 v5, 0x80, v4
	v_xor_b32_e32 v6, 64, v4
	v_xor_b32_e32 v7, 32, v4
	v_xor_b32_e32 v8, 16, v4
	v_xor_b32_e32 v9, 8, v4
	v_xor_b32_e32 v10, 4, v4
	v_mov_b32_e32 v11, 0x358637bd
	s_add_i32 s2, s2, s74
	s_mov_b32 s3, s50
	s_add_u32 s18, s18, 0x2000
	s_addc_u32 s19, s19, 0
	s_add_u32 s24, s96, 0x20cc0000
	s_addc_u32 s25, s97, 0
	s_cmp_ge_u32 s2, 0x2080
	s_cbranch_scc1 .Lp10_done
	global_load_dwordx4 v[12:15], v1, s[18:19]
	global_load_dwordx4 v[16:19], v1, s[18:19] offset:16
	global_load_dwordx4 v[20:23], v1, s[18:19] offset:2048
	global_load_dwordx4 v[24:27], v1, s[18:19] offset:2064
	global_load_dwordx4 v[28:31], v2, s[18:19]
	global_load_dwordx4 v[32:35], v2, s[18:19] offset:16
	global_load_dwordx4 v[36:39], v2, s[18:19] offset:2048
	global_load_dwordx4 v[40:43], v2, s[18:19] offset:2064
	s_lshl_b32 s4, s2, 12
	s_add_u32 s6, s24, s4
	s_addc_u32 s7, s25, 0
	s_lshl_b32 s4, s2, 13
	s_add_u32 s8, s22, s4
	s_addc_u32 s9, s23, 0
	global_load_dwordx4 v[44:47], v0, s[6:7]
	global_load_dwordx4 v[48:51], v0, s[6:7] offset:1024
	global_load_dwordx4 v[52:55], v0, s[6:7] offset:2048
	global_load_dwordx4 v[56:59], v0, s[6:7] offset:3072
	global_load_dwordx4 v[60:63], v1, s[8:9]
	global_load_dwordx4 v[64:67], v1, s[8:9] offset:16
	global_load_dwordx4 v[68:71], v1, s[8:9] offset:2048
	global_load_dwordx4 v[72:75], v1, s[8:9] offset:2064
	global_load_dwordx4 v[76:79], v2, s[8:9]
	global_load_dwordx4 v[80:83], v2, s[8:9] offset:16
	global_load_dwordx4 v[84:87], v2, s[8:9] offset:2048
	global_load_dwordx4 v[88:91], v2, s[8:9] offset:2064
	s_add_u32 s30, s2, s3
	s_cmp_ge_u32 s30, 0x2080
	s_cbranch_scc1 .Lp10_p0
	s_lshl_b32 s4, s30, 12
	s_add_u32 s6, s24, s4
	s_addc_u32 s7, s25, 0
	s_lshl_b32 s4, s30, 13
	s_add_u32 s8, s22, s4
	s_addc_u32 s9, s23, 0
	global_load_dwordx4 v[92:95], v0, s[6:7]
	global_load_dwordx4 v[96:99], v0, s[6:7] offset:1024
	global_load_dwordx4 v[100:103], v0, s[6:7] offset:2048
	global_load_dwordx4 v[104:107], v0, s[6:7] offset:3072
	global_load_dwordx4 v[108:111], v1, s[8:9]
	global_load_dwordx4 v[112:115], v1, s[8:9] offset:16
	global_load_dwordx4 v[116:119], v1, s[8:9] offset:2048
	global_load_dwordx4 v[120:123], v1, s[8:9] offset:2064
	global_load_dwordx4 v[124:127], v2, s[8:9]
	global_load_dwordx4 v[128:131], v2, s[8:9] offset:16
	global_load_dwordx4 v[132:135], v2, s[8:9] offset:2048
	global_load_dwordx4 v[136:139], v2, s[8:9] offset:2064
.Lp10_p0:
	s_lshl_b32 s29, s3, 1
	s_add_u32 s29, s29, s2
	s_add_u32 s30, s2, s3
	s_cmp_ge_u32 s29, 0x2080
	s_cbranch_scc1 .Lp10_n1
	s_lshl_b32 s4, s29, 12
	s_add_u32 s6, s24, s4
	s_addc_u32 s7, s25, 0
	s_lshl_b32 s4, s29, 13
	s_add_u32 s8, s22, s4
	s_addc_u32 s9, s23, 0
	global_load_dwordx4 v[140:143], v0, s[6:7]
	global_load_dwordx4 v[144:147], v0, s[6:7] offset:1024
	global_load_dwordx4 v[148:151], v0, s[6:7] offset:2048
	global_load_dwordx4 v[152:155], v0, s[6:7] offset:3072
	global_load_dwordx4 v[156:159], v1, s[8:9]
	global_load_dwordx4 v[160:163], v1, s[8:9] offset:16
	global_load_dwordx4 v[164:167], v1, s[8:9] offset:2048
	global_load_dwordx4 v[168:171], v1, s[8:9] offset:2064
	global_load_dwordx4 v[172:175], v2, s[8:9]
	global_load_dwordx4 v[176:179], v2, s[8:9] offset:16
	global_load_dwordx4 v[180:183], v2, s[8:9] offset:2048
	global_load_dwordx4 v[184:187], v2, s[8:9] offset:2064
	s_waitcnt vmcnt(24)
	s_branch .Lp10_g1
.Lp10_n1:
	s_cmp_ge_u32 s30, 0x2080
	s_cbranch_scc1 .Lp10_z1
	s_waitcnt vmcnt(12)
	s_branch .Lp10_g1

.Lp10_g1:
	v_lshlrev_b32_e32 v188, 16, v44
	v_and_b32_e32 v189, 0xffff0000, v44
	v_lshlrev_b32_e32 v190, 16, v45
	v_and_b32_e32 v191, 0xffff0000, v45
	v_lshlrev_b32_e32 v192, 16, v46
	v_and_b32_e32 v193, 0xffff0000, v46
	v_lshlrev_b32_e32 v194, 16, v47
	v_and_b32_e32 v195, 0xffff0000, v47
	v_lshlrev_b32_e32 v196, 16, v48
	v_and_b32_e32 v197, 0xffff0000, v48
	v_lshlrev_b32_e32 v198, 16, v49
	v_and_b32_e32 v199, 0xffff0000, v49
	v_lshlrev_b32_e32 v200, 16, v50
	v_and_b32_e32 v201, 0xffff0000, v50
	v_lshlrev_b32_e32 v202, 16, v51
	v_and_b32_e32 v203, 0xffff0000, v51
	v_lshlrev_b32_e32 v204, 16, v52
	v_and_b32_e32 v205, 0xffff0000, v52
	v_lshlrev_b32_e32 v206, 16, v53
	v_and_b32_e32 v207, 0xffff0000, v53
	v_lshlrev_b32_e32 v210, 16, v54
	v_and_b32_e32 v211, 0xffff0000, v54
	v_lshlrev_b32_e32 v212, 16, v55
	v_and_b32_e32 v213, 0xffff0000, v55
	v_lshlrev_b32_e32 v214, 16, v56
	v_and_b32_e32 v215, 0xffff0000, v56
	v_lshlrev_b32_e32 v216, 16, v57
	v_and_b32_e32 v217, 0xffff0000, v57
	v_lshlrev_b32_e32 v218, 16, v58
	v_and_b32_e32 v219, 0xffff0000, v58
	v_lshlrev_b32_e32 v220, 16, v59
	v_and_b32_e32 v221, 0xffff0000, v59
	v_mul_f32_e32 v222, v188, v188
	v_mul_f32_e32 v223, v189, v189
	v_mul_f32_e32 v224, v190, v190
	v_mul_f32_e32 v225, v191, v191
	v_fmac_f32_e32 v222, v192, v192
	v_fmac_f32_e32 v223, v193, v193
	v_fmac_f32_e32 v224, v194, v194
	v_fmac_f32_e32 v225, v195, v195
	v_fmac_f32_e32 v222, v196, v196
	v_fmac_f32_e32 v223, v197, v197
	v_fmac_f32_e32 v224, v198, v198
	v_fmac_f32_e32 v225, v199, v199
	v_fmac_f32_e32 v222, v200, v200
	v_fmac_f32_e32 v223, v201, v201
	v_fmac_f32_e32 v224, v202, v202
	v_fmac_f32_e32 v225, v203, v203
	v_fmac_f32_e32 v222, v204, v204
	v_fmac_f32_e32 v223, v205, v205
	v_fmac_f32_e32 v224, v206, v206
	v_fmac_f32_e32 v225, v207, v207
	v_fmac_f32_e32 v222, v210, v210
	v_fmac_f32_e32 v223, v211, v211
	v_fmac_f32_e32 v224, v212, v212
	v_fmac_f32_e32 v225, v213, v213
	v_fmac_f32_e32 v222, v214, v214
	v_fmac_f32_e32 v223, v215, v215
	v_fmac_f32_e32 v224, v216, v216
	v_fmac_f32_e32 v225, v217, v217
	v_fmac_f32_e32 v222, v218, v218
	v_fmac_f32_e32 v223, v219, v219
	v_fmac_f32_e32 v224, v220, v220
	v_fmac_f32_e32 v225, v221, v221
	v_add_f32_e32 v222, v222, v223
	v_add_f32_e32 v224, v224, v225
	v_add_f32_e32 v222, v222, v224
	ds_bpermute_b32 v226, v5, v222
	s_waitcnt lgkmcnt(0)
	v_add_f32_e32 v222, v222, v226
	ds_bpermute_b32 v226, v6, v222
	s_waitcnt lgkmcnt(0)
	v_add_f32_e32 v222, v222, v226
	ds_bpermute_b32 v226, v7, v222
	s_waitcnt lgkmcnt(0)
	v_add_f32_e32 v222, v222, v226
	ds_bpermute_b32 v226, v8, v222
	s_waitcnt lgkmcnt(0)
	v_add_f32_e32 v222, v222, v226
	ds_bpermute_b32 v226, v9, v222
	s_waitcnt lgkmcnt(0)
	v_add_f32_e32 v222, v222, v226
	ds_bpermute_b32 v226, v10, v222
	s_waitcnt lgkmcnt(0)
	v_add_f32_e32 v222, v222, v226
	v_fmamk_f32 v222, v222, 0x3a000000, v11
	v_rsq_f32_e32 v227, v222
	s_nop 0
	v_mul_f32_e32 v188, v188, v227
	v_fmac_f32_e32 v60, v188, v12
	v_mul_f32_e32 v189, v189, v227
	v_fmac_f32_e32 v61, v189, v13
	v_mul_f32_e32 v190, v190, v227
	v_fmac_f32_e32 v62, v190, v14
	v_mul_f32_e32 v191, v191, v227
	v_fmac_f32_e32 v63, v191, v15
	v_mul_f32_e32 v192, v192, v227
	v_fmac_f32_e32 v64, v192, v16
	v_mul_f32_e32 v193, v193, v227
	v_fmac_f32_e32 v65, v193, v17
	v_mul_f32_e32 v194, v194, v227
	v_fmac_f32_e32 v66, v194, v18
	v_mul_f32_e32 v195, v195, v227
	v_fmac_f32_e32 v67, v195, v19
	v_mul_f32_e32 v196, v196, v227
	v_fmac_f32_e32 v68, v196, v20
	v_mul_f32_e32 v197, v197, v227
	v_fmac_f32_e32 v69, v197, v21
	v_mul_f32_e32 v198, v198, v227
	v_fmac_f32_e32 v70, v198, v22
	v_mul_f32_e32 v199, v199, v227
	v_fmac_f32_e32 v71, v199, v23
	v_mul_f32_e32 v200, v200, v227
	v_fmac_f32_e32 v72, v200, v24
	v_mul_f32_e32 v201, v201, v227
	v_fmac_f32_e32 v73, v201, v25
	v_mul_f32_e32 v202, v202, v227
	v_fmac_f32_e32 v74, v202, v26
	v_mul_f32_e32 v203, v203, v227
	v_fmac_f32_e32 v75, v203, v27
	v_mul_f32_e32 v204, v204, v227
	v_fmac_f32_e32 v76, v204, v28
	v_mul_f32_e32 v205, v205, v227
	v_fmac_f32_e32 v77, v205, v29
	v_mul_f32_e32 v206, v206, v227
	v_fmac_f32_e32 v78, v206, v30
	v_mul_f32_e32 v207, v207, v227
	v_fmac_f32_e32 v79, v207, v31
	v_mul_f32_e32 v210, v210, v227
	v_fmac_f32_e32 v80, v210, v32
	v_mul_f32_e32 v211, v211, v227
	v_fmac_f32_e32 v81, v211, v33
	v_mul_f32_e32 v212, v212, v227
	v_fmac_f32_e32 v82, v212, v34
	v_mul_f32_e32 v213, v213, v227
	v_fmac_f32_e32 v83, v213, v35
	v_mul_f32_e32 v214, v214, v227
	v_fmac_f32_e32 v84, v214, v36
	v_mul_f32_e32 v215, v215, v227
	v_fmac_f32_e32 v85, v215, v37
	v_mul_f32_e32 v216, v216, v227
	v_fmac_f32_e32 v86, v216, v38
	v_mul_f32_e32 v217, v217, v227
	v_fmac_f32_e32 v87, v217, v39
	v_mul_f32_e32 v218, v218, v227
	v_fmac_f32_e32 v88, v218, v40
	v_mul_f32_e32 v219, v219, v227
	v_fmac_f32_e32 v89, v219, v41
	v_mul_f32_e32 v220, v220, v227
	v_fmac_f32_e32 v90, v220, v42
	v_mul_f32_e32 v221, v221, v227
	v_fmac_f32_e32 v91, v221, v43
	s_lshl_b32 s4, s2, 13
	s_add_u32 s14, s22, s4
	s_addc_u32 s15, s23, 0
	global_store_dwordx4 v1, v[60:63], s[14:15]
	global_store_dwordx4 v1, v[64:67], s[14:15] offset:16
	global_store_dwordx4 v1, v[68:71], s[14:15] offset:2048
	global_store_dwordx4 v1, v[72:75], s[14:15] offset:2064
	global_store_dwordx4 v2, v[76:79], s[14:15]
	global_store_dwordx4 v2, v[80:83], s[14:15] offset:16
	global_store_dwordx4 v2, v[84:87], s[14:15] offset:2048
	global_store_dwordx4 v2, v[88:91], s[14:15] offset:2064
	s_mov_b32 s2, s30
	s_cmp_ge_u32 s2, 0x2080
	s_cbranch_scc1 .Lp10_done
.Lp10_p1:
	s_lshl_b32 s29, s3, 1
	s_add_u32 s29, s29, s2
	s_add_u32 s30, s2, s3
	s_cmp_ge_u32 s29, 0x2080
	s_cbranch_scc1 .Lp10_n2
	s_lshl_b32 s4, s29, 12
	s_add_u32 s6, s24, s4
	s_addc_u32 s7, s25, 0
	s_lshl_b32 s4, s29, 13
	s_add_u32 s8, s22, s4
	s_addc_u32 s9, s23, 0
	global_load_dwordx4 v[44:47], v0, s[6:7]
	global_load_dwordx4 v[48:51], v0, s[6:7] offset:1024
	global_load_dwordx4 v[52:55], v0, s[6:7] offset:2048
	global_load_dwordx4 v[56:59], v0, s[6:7] offset:3072
	global_load_dwordx4 v[60:63], v1, s[8:9]
	global_load_dwordx4 v[64:67], v1, s[8:9] offset:16
	global_load_dwordx4 v[68:71], v1, s[8:9] offset:2048
	global_load_dwordx4 v[72:75], v1, s[8:9] offset:2064
	global_load_dwordx4 v[76:79], v2, s[8:9]
	global_load_dwordx4 v[80:83], v2, s[8:9] offset:16
	global_load_dwordx4 v[84:87], v2, s[8:9] offset:2048
	global_load_dwordx4 v[88:91], v2, s[8:9] offset:2064
	s_waitcnt vmcnt(32)
	s_branch .Lp10_g2
.Lp10_n2:
	s_cmp_ge_u32 s30, 0x2080
	s_cbranch_scc1 .Lp10_z2
	s_waitcnt vmcnt(20)
	s_branch .Lp10_g2

.Lp10_g2:
	v_lshlrev_b32_e32 v188, 16, v92
	v_and_b32_e32 v189, 0xffff0000, v92
	v_lshlrev_b32_e32 v190, 16, v93
	v_and_b32_e32 v191, 0xffff0000, v93
	v_lshlrev_b32_e32 v192, 16, v94
	v_and_b32_e32 v193, 0xffff0000, v94
	v_lshlrev_b32_e32 v194, 16, v95
	v_and_b32_e32 v195, 0xffff0000, v95
	v_lshlrev_b32_e32 v196, 16, v96
	v_and_b32_e32 v197, 0xffff0000, v96
	v_lshlrev_b32_e32 v198, 16, v97
	v_and_b32_e32 v199, 0xffff0000, v97
	v_lshlrev_b32_e32 v200, 16, v98
	v_and_b32_e32 v201, 0xffff0000, v98
	v_lshlrev_b32_e32 v202, 16, v99
	v_and_b32_e32 v203, 0xffff0000, v99
	v_lshlrev_b32_e32 v204, 16, v100
	v_and_b32_e32 v205, 0xffff0000, v100
	v_lshlrev_b32_e32 v206, 16, v101
	v_and_b32_e32 v207, 0xffff0000, v101
	v_lshlrev_b32_e32 v210, 16, v102
	v_and_b32_e32 v211, 0xffff0000, v102
	v_lshlrev_b32_e32 v212, 16, v103
	v_and_b32_e32 v213, 0xffff0000, v103
	v_lshlrev_b32_e32 v214, 16, v104
	v_and_b32_e32 v215, 0xffff0000, v104
	v_lshlrev_b32_e32 v216, 16, v105
	v_and_b32_e32 v217, 0xffff0000, v105
	v_lshlrev_b32_e32 v218, 16, v106
	v_and_b32_e32 v219, 0xffff0000, v106
	v_lshlrev_b32_e32 v220, 16, v107
	v_and_b32_e32 v221, 0xffff0000, v107
	v_mul_f32_e32 v222, v188, v188
	v_mul_f32_e32 v223, v189, v189
	v_mul_f32_e32 v224, v190, v190
	v_mul_f32_e32 v225, v191, v191
	v_fmac_f32_e32 v222, v192, v192
	v_fmac_f32_e32 v223, v193, v193
	v_fmac_f32_e32 v224, v194, v194
	v_fmac_f32_e32 v225, v195, v195
	v_fmac_f32_e32 v222, v196, v196
	v_fmac_f32_e32 v223, v197, v197
	v_fmac_f32_e32 v224, v198, v198
	v_fmac_f32_e32 v225, v199, v199
	v_fmac_f32_e32 v222, v200, v200
	v_fmac_f32_e32 v223, v201, v201
	v_fmac_f32_e32 v224, v202, v202
	v_fmac_f32_e32 v225, v203, v203
	v_fmac_f32_e32 v222, v204, v204
	v_fmac_f32_e32 v223, v205, v205
	v_fmac_f32_e32 v224, v206, v206
	v_fmac_f32_e32 v225, v207, v207
	v_fmac_f32_e32 v222, v210, v210
	v_fmac_f32_e32 v223, v211, v211
	v_fmac_f32_e32 v224, v212, v212
	v_fmac_f32_e32 v225, v213, v213
	v_fmac_f32_e32 v222, v214, v214
	v_fmac_f32_e32 v223, v215, v215
	v_fmac_f32_e32 v224, v216, v216
	v_fmac_f32_e32 v225, v217, v217
	v_fmac_f32_e32 v222, v218, v218
	v_fmac_f32_e32 v223, v219, v219
	v_fmac_f32_e32 v224, v220, v220
	v_fmac_f32_e32 v225, v221, v221
	v_add_f32_e32 v222, v222, v223
	v_add_f32_e32 v224, v224, v225
	v_add_f32_e32 v222, v222, v224
	ds_bpermute_b32 v226, v5, v222
	s_waitcnt lgkmcnt(0)
	v_add_f32_e32 v222, v222, v226
	ds_bpermute_b32 v226, v6, v222
	s_waitcnt lgkmcnt(0)
	v_add_f32_e32 v222, v222, v226
	ds_bpermute_b32 v226, v7, v222
	s_waitcnt lgkmcnt(0)
	v_add_f32_e32 v222, v222, v226
	ds_bpermute_b32 v226, v8, v222
	s_waitcnt lgkmcnt(0)
	v_add_f32_e32 v222, v222, v226
	ds_bpermute_b32 v226, v9, v222
	s_waitcnt lgkmcnt(0)
	v_add_f32_e32 v222, v222, v226
	ds_bpermute_b32 v226, v10, v222
	s_waitcnt lgkmcnt(0)
	v_add_f32_e32 v222, v222, v226
	v_fmamk_f32 v222, v222, 0x3a000000, v11
	v_rsq_f32_e32 v227, v222
	s_nop 0
	v_mul_f32_e32 v188, v188, v227
	v_fmac_f32_e32 v108, v188, v12
	v_mul_f32_e32 v189, v189, v227
	v_fmac_f32_e32 v109, v189, v13
	v_mul_f32_e32 v190, v190, v227
	v_fmac_f32_e32 v110, v190, v14
	v_mul_f32_e32 v191, v191, v227
	v_fmac_f32_e32 v111, v191, v15
	v_mul_f32_e32 v192, v192, v227
	v_fmac_f32_e32 v112, v192, v16
	v_mul_f32_e32 v193, v193, v227
	v_fmac_f32_e32 v113, v193, v17
	v_mul_f32_e32 v194, v194, v227
	v_fmac_f32_e32 v114, v194, v18
	v_mul_f32_e32 v195, v195, v227
	v_fmac_f32_e32 v115, v195, v19
	v_mul_f32_e32 v196, v196, v227
	v_fmac_f32_e32 v116, v196, v20
	v_mul_f32_e32 v197, v197, v227
	v_fmac_f32_e32 v117, v197, v21
	v_mul_f32_e32 v198, v198, v227
	v_fmac_f32_e32 v118, v198, v22
	v_mul_f32_e32 v199, v199, v227
	v_fmac_f32_e32 v119, v199, v23
	v_mul_f32_e32 v200, v200, v227
	v_fmac_f32_e32 v120, v200, v24
	v_mul_f32_e32 v201, v201, v227
	v_fmac_f32_e32 v121, v201, v25
	v_mul_f32_e32 v202, v202, v227
	v_fmac_f32_e32 v122, v202, v26
	v_mul_f32_e32 v203, v203, v227
	v_fmac_f32_e32 v123, v203, v27
	v_mul_f32_e32 v204, v204, v227
	v_fmac_f32_e32 v124, v204, v28
	v_mul_f32_e32 v205, v205, v227
	v_fmac_f32_e32 v125, v205, v29
	v_mul_f32_e32 v206, v206, v227
	v_fmac_f32_e32 v126, v206, v30
	v_mul_f32_e32 v207, v207, v227
	v_fmac_f32_e32 v127, v207, v31
	v_mul_f32_e32 v210, v210, v227
	v_fmac_f32_e32 v128, v210, v32
	v_mul_f32_e32 v211, v211, v227
	v_fmac_f32_e32 v129, v211, v33
	v_mul_f32_e32 v212, v212, v227
	v_fmac_f32_e32 v130, v212, v34
	v_mul_f32_e32 v213, v213, v227
	v_fmac_f32_e32 v131, v213, v35
	v_mul_f32_e32 v214, v214, v227
	v_fmac_f32_e32 v132, v214, v36
	v_mul_f32_e32 v215, v215, v227
	v_fmac_f32_e32 v133, v215, v37
	v_mul_f32_e32 v216, v216, v227
	v_fmac_f32_e32 v134, v216, v38
	v_mul_f32_e32 v217, v217, v227
	v_fmac_f32_e32 v135, v217, v39
	v_mul_f32_e32 v218, v218, v227
	v_fmac_f32_e32 v136, v218, v40
	v_mul_f32_e32 v219, v219, v227
	v_fmac_f32_e32 v137, v219, v41
	v_mul_f32_e32 v220, v220, v227
	v_fmac_f32_e32 v138, v220, v42
	v_mul_f32_e32 v221, v221, v227
	v_fmac_f32_e32 v139, v221, v43
	s_lshl_b32 s4, s2, 13
	s_add_u32 s14, s22, s4
	s_addc_u32 s15, s23, 0
	global_store_dwordx4 v1, v[108:111], s[14:15]
	global_store_dwordx4 v1, v[112:115], s[14:15] offset:16
	global_store_dwordx4 v1, v[116:119], s[14:15] offset:2048
	global_store_dwordx4 v1, v[120:123], s[14:15] offset:2064
	global_store_dwordx4 v2, v[124:127], s[14:15]
	global_store_dwordx4 v2, v[128:131], s[14:15] offset:16
	global_store_dwordx4 v2, v[132:135], s[14:15] offset:2048
	global_store_dwordx4 v2, v[136:139], s[14:15] offset:2064
	s_mov_b32 s2, s30
	s_cmp_ge_u32 s2, 0x2080
	s_cbranch_scc1 .Lp10_done
.Lp10_l0:
	s_lshl_b32 s29, s3, 1
	s_add_u32 s29, s29, s2
	s_add_u32 s30, s2, s3
	s_cmp_ge_u32 s29, 0x2080
	s_cbranch_scc1 .Lp10_n3
	s_lshl_b32 s4, s29, 12
	s_add_u32 s6, s24, s4
	s_addc_u32 s7, s25, 0
	s_lshl_b32 s4, s29, 13
	s_add_u32 s8, s22, s4
	s_addc_u32 s9, s23, 0
	global_load_dwordx4 v[92:95], v0, s[6:7]
	global_load_dwordx4 v[96:99], v0, s[6:7] offset:1024
	global_load_dwordx4 v[100:103], v0, s[6:7] offset:2048
	global_load_dwordx4 v[104:107], v0, s[6:7] offset:3072
	global_load_dwordx4 v[108:111], v1, s[8:9]
	global_load_dwordx4 v[112:115], v1, s[8:9] offset:16
	global_load_dwordx4 v[116:119], v1, s[8:9] offset:2048
	global_load_dwordx4 v[120:123], v1, s[8:9] offset:2064
	global_load_dwordx4 v[124:127], v2, s[8:9]
	global_load_dwordx4 v[128:131], v2, s[8:9] offset:16
	global_load_dwordx4 v[132:135], v2, s[8:9] offset:2048
	global_load_dwordx4 v[136:139], v2, s[8:9] offset:2064
	s_waitcnt vmcnt(40)
	s_branch .Lp10_g3
.Lp10_n3:
	s_cmp_ge_u32 s30, 0x2080
	s_cbranch_scc1 .Lp10_z3
	s_waitcnt vmcnt(28)
	s_branch .Lp10_g3
.Lp10_z3:
	s_waitcnt vmcnt(16)
.Lp10_g3:
	v_lshlrev_b32_e32 v188, 16, v140
	v_and_b32_e32 v189, 0xffff0000, v140
	v_lshlrev_b32_e32 v190, 16, v141
	v_and_b32_e32 v191, 0xffff0000, v141
	v_lshlrev_b32_e32 v192, 16, v142
	v_and_b32_e32 v193, 0xffff0000, v142
	v_lshlrev_b32_e32 v194, 16, v143
	v_and_b32_e32 v195, 0xffff0000, v143
	v_lshlrev_b32_e32 v196, 16, v144
	v_and_b32_e32 v197, 0xffff0000, v144
	v_lshlrev_b32_e32 v198, 16, v145
	v_and_b32_e32 v199, 0xffff0000, v145
	v_lshlrev_b32_e32 v200, 16, v146
	v_and_b32_e32 v201, 0xffff0000, v146
	v_lshlrev_b32_e32 v202, 16, v147
	v_and_b32_e32 v203, 0xffff0000, v147
	v_lshlrev_b32_e32 v204, 16, v148
	v_and_b32_e32 v205, 0xffff0000, v148
	v_lshlrev_b32_e32 v206, 16, v149
	v_and_b32_e32 v207, 0xffff0000, v149
	v_lshlrev_b32_e32 v210, 16, v150
	v_and_b32_e32 v211, 0xffff0000, v150
	v_lshlrev_b32_e32 v212, 16, v151
	v_and_b32_e32 v213, 0xffff0000, v151
	v_lshlrev_b32_e32 v214, 16, v152
	v_and_b32_e32 v215, 0xffff0000, v152
	v_lshlrev_b32_e32 v216, 16, v153
	v_and_b32_e32 v217, 0xffff0000, v153
	v_lshlrev_b32_e32 v218, 16, v154
	v_and_b32_e32 v219, 0xffff0000, v154
	v_lshlrev_b32_e32 v220, 16, v155
	v_and_b32_e32 v221, 0xffff0000, v155
	v_mul_f32_e32 v222, v188, v188
	v_mul_f32_e32 v223, v189, v189
	v_mul_f32_e32 v224, v190, v190
	v_mul_f32_e32 v225, v191, v191
	v_fmac_f32_e32 v222, v192, v192
	v_fmac_f32_e32 v223, v193, v193
	v_fmac_f32_e32 v224, v194, v194
	v_fmac_f32_e32 v225, v195, v195
	v_fmac_f32_e32 v222, v196, v196
	v_fmac_f32_e32 v223, v197, v197
	v_fmac_f32_e32 v224, v198, v198
	v_fmac_f32_e32 v225, v199, v199
	v_fmac_f32_e32 v222, v200, v200
	v_fmac_f32_e32 v223, v201, v201
	v_fmac_f32_e32 v224, v202, v202
	v_fmac_f32_e32 v225, v203, v203
	v_fmac_f32_e32 v222, v204, v204
	v_fmac_f32_e32 v223, v205, v205
	v_fmac_f32_e32 v224, v206, v206
	v_fmac_f32_e32 v225, v207, v207
	v_fmac_f32_e32 v222, v210, v210
	v_fmac_f32_e32 v223, v211, v211
	v_fmac_f32_e32 v224, v212, v212
	v_fmac_f32_e32 v225, v213, v213
	v_fmac_f32_e32 v222, v214, v214
	v_fmac_f32_e32 v223, v215, v215
	v_fmac_f32_e32 v224, v216, v216
	v_fmac_f32_e32 v225, v217, v217
	v_fmac_f32_e32 v222, v218, v218
	v_fmac_f32_e32 v223, v219, v219
	v_fmac_f32_e32 v224, v220, v220
	v_fmac_f32_e32 v225, v221, v221
	v_add_f32_e32 v222, v222, v223
	v_add_f32_e32 v224, v224, v225
	v_add_f32_e32 v222, v222, v224
	ds_bpermute_b32 v226, v5, v222
	s_waitcnt lgkmcnt(0)
	v_add_f32_e32 v222, v222, v226
	ds_bpermute_b32 v226, v6, v222
	s_waitcnt lgkmcnt(0)
	v_add_f32_e32 v222, v222, v226
	ds_bpermute_b32 v226, v7, v222
	s_waitcnt lgkmcnt(0)
	v_add_f32_e32 v222, v222, v226
	ds_bpermute_b32 v226, v8, v222
	s_waitcnt lgkmcnt(0)
	v_add_f32_e32 v222, v222, v226
	ds_bpermute_b32 v226, v9, v222
	s_waitcnt lgkmcnt(0)
	v_add_f32_e32 v222, v222, v226
	ds_bpermute_b32 v226, v10, v222
	s_waitcnt lgkmcnt(0)
	v_add_f32_e32 v222, v222, v226
	v_fmamk_f32 v222, v222, 0x3a000000, v11
	v_rsq_f32_e32 v227, v222
	s_nop 0
	v_mul_f32_e32 v188, v188, v227
	v_fmac_f32_e32 v156, v188, v12
	v_mul_f32_e32 v189, v189, v227
	v_fmac_f32_e32 v157, v189, v13
	v_mul_f32_e32 v190, v190, v227
	v_fmac_f32_e32 v158, v190, v14
	v_mul_f32_e32 v191, v191, v227
	v_fmac_f32_e32 v159, v191, v15
	v_mul_f32_e32 v192, v192, v227
	v_fmac_f32_e32 v160, v192, v16
	v_mul_f32_e32 v193, v193, v227
	v_fmac_f32_e32 v161, v193, v17
	v_mul_f32_e32 v194, v194, v227
	v_fmac_f32_e32 v162, v194, v18
	v_mul_f32_e32 v195, v195, v227
	v_fmac_f32_e32 v163, v195, v19
	v_mul_f32_e32 v196, v196, v227
	v_fmac_f32_e32 v164, v196, v20
	v_mul_f32_e32 v197, v197, v227
	v_fmac_f32_e32 v165, v197, v21
	v_mul_f32_e32 v198, v198, v227
	v_fmac_f32_e32 v166, v198, v22
	v_mul_f32_e32 v199, v199, v227
	v_fmac_f32_e32 v167, v199, v23
	v_mul_f32_e32 v200, v200, v227
	v_fmac_f32_e32 v168, v200, v24
	v_mul_f32_e32 v201, v201, v227
	v_fmac_f32_e32 v169, v201, v25
	v_mul_f32_e32 v202, v202, v227
	v_fmac_f32_e32 v170, v202, v26
	v_mul_f32_e32 v203, v203, v227
	v_fmac_f32_e32 v171, v203, v27
	v_mul_f32_e32 v204, v204, v227
	v_fmac_f32_e32 v172, v204, v28
	v_mul_f32_e32 v205, v205, v227
	v_fmac_f32_e32 v173, v205, v29
	v_mul_f32_e32 v206, v206, v227
	v_fmac_f32_e32 v174, v206, v30
	v_mul_f32_e32 v207, v207, v227
	v_fmac_f32_e32 v175, v207, v31
	v_mul_f32_e32 v210, v210, v227
	v_fmac_f32_e32 v176, v210, v32
	v_mul_f32_e32 v211, v211, v227
	v_fmac_f32_e32 v177, v211, v33
	v_mul_f32_e32 v212, v212, v227
	v_fmac_f32_e32 v178, v212, v34
	v_mul_f32_e32 v213, v213, v227
	v_fmac_f32_e32 v179, v213, v35
	v_mul_f32_e32 v214, v214, v227
	v_fmac_f32_e32 v180, v214, v36
	v_mul_f32_e32 v215, v215, v227
	v_fmac_f32_e32 v181, v215, v37
	v_mul_f32_e32 v216, v216, v227
	v_fmac_f32_e32 v182, v216, v38
	v_mul_f32_e32 v217, v217, v227
	v_fmac_f32_e32 v183, v217, v39
	v_mul_f32_e32 v218, v218, v227
	v_fmac_f32_e32 v184, v218, v40
	v_mul_f32_e32 v219, v219, v227
	v_fmac_f32_e32 v185, v219, v41
	v_mul_f32_e32 v220, v220, v227
	v_fmac_f32_e32 v186, v220, v42
	v_mul_f32_e32 v221, v221, v227
	v_fmac_f32_e32 v187, v221, v43
	s_lshl_b32 s4, s2, 13
	s_add_u32 s14, s22, s4
	s_addc_u32 s15, s23, 0
	global_store_dwordx4 v1, v[156:159], s[14:15]
	global_store_dwordx4 v1, v[160:163], s[14:15] offset:16
	global_store_dwordx4 v1, v[164:167], s[14:15] offset:2048
	global_store_dwordx4 v1, v[168:171], s[14:15] offset:2064
	global_store_dwordx4 v2, v[172:175], s[14:15]
	global_store_dwordx4 v2, v[176:179], s[14:15] offset:16
	global_store_dwordx4 v2, v[180:183], s[14:15] offset:2048
	global_store_dwordx4 v2, v[184:187], s[14:15] offset:2064
	s_mov_b32 s2, s30
	s_cmp_ge_u32 s2, 0x2080
	s_cbranch_scc1 .Lp10_done
.Lp10_l1:
	s_lshl_b32 s29, s3, 1
	s_add_u32 s29, s29, s2
	s_add_u32 s30, s2, s3
	s_cmp_ge_u32 s29, 0x2080
	s_cbranch_scc1 .Lp10_n4
	s_lshl_b32 s4, s29, 12
	s_add_u32 s6, s24, s4
	s_addc_u32 s7, s25, 0
	s_lshl_b32 s4, s29, 13
	s_add_u32 s8, s22, s4
	s_addc_u32 s9, s23, 0
	global_load_dwordx4 v[140:143], v0, s[6:7]
	global_load_dwordx4 v[144:147], v0, s[6:7] offset:1024
	global_load_dwordx4 v[148:151], v0, s[6:7] offset:2048
	global_load_dwordx4 v[152:155], v0, s[6:7] offset:3072
	global_load_dwordx4 v[156:159], v1, s[8:9]
	global_load_dwordx4 v[160:163], v1, s[8:9] offset:16
	global_load_dwordx4 v[164:167], v1, s[8:9] offset:2048
	global_load_dwordx4 v[168:171], v1, s[8:9] offset:2064
	global_load_dwordx4 v[172:175], v2, s[8:9]
	global_load_dwordx4 v[176:179], v2, s[8:9] offset:16
	global_load_dwordx4 v[180:183], v2, s[8:9] offset:2048
	global_load_dwordx4 v[184:187], v2, s[8:9] offset:2064
	s_waitcnt vmcnt(40)
	s_branch .Lp10_g4

.Lp10_l2:
	s_lshl_b32 s29, s3, 1
	s_add_u32 s29, s29, s2
	s_add_u32 s30, s2, s3
	s_cmp_ge_u32 s29, 0x2080
	s_cbranch_scc1 .Lp10_n5
	s_lshl_b32 s4, s29, 12
	s_add_u32 s6, s24, s4
	s_addc_u32 s7, s25, 0
	s_lshl_b32 s4, s29, 13
	s_add_u32 s8, s22, s4
	s_addc_u32 s9, s23, 0
	global_load_dwordx4 v[44:47], v0, s[6:7]
	global_load_dwordx4 v[48:51], v0, s[6:7] offset:1024
	global_load_dwordx4 v[52:55], v0, s[6:7] offset:2048
	global_load_dwordx4 v[56:59], v0, s[6:7] offset:3072
	global_load_dwordx4 v[60:63], v1, s[8:9]
	global_load_dwordx4 v[64:67], v1, s[8:9] offset:16
	global_load_dwordx4 v[68:71], v1, s[8:9] offset:2048
	global_load_dwordx4 v[72:75], v1, s[8:9] offset:2064
	global_load_dwordx4 v[76:79], v2, s[8:9]
	global_load_dwordx4 v[80:83], v2, s[8:9] offset:16
	global_load_dwordx4 v[84:87], v2, s[8:9] offset:2048
	global_load_dwordx4 v[88:91], v2, s[8:9] offset:2064
	s_waitcnt vmcnt(40)
	s_branch .Lp10_g5

.Lp10_g5:
	v_lshlrev_b32_e32 v188, 16, v92
	v_and_b32_e32 v189, 0xffff0000, v92
	v_lshlrev_b32_e32 v190, 16, v93
	v_and_b32_e32 v191, 0xffff0000, v93
	v_lshlrev_b32_e32 v192, 16, v94
	v_and_b32_e32 v193, 0xffff0000, v94
	v_lshlrev_b32_e32 v194, 16, v95
	v_and_b32_e32 v195, 0xffff0000, v95
	v_lshlrev_b32_e32 v196, 16, v96
	v_and_b32_e32 v197, 0xffff0000, v96
	v_lshlrev_b32_e32 v198, 16, v97
	v_and_b32_e32 v199, 0xffff0000, v97
	v_lshlrev_b32_e32 v200, 16, v98
	v_and_b32_e32 v201, 0xffff0000, v98
	v_lshlrev_b32_e32 v202, 16, v99
	v_and_b32_e32 v203, 0xffff0000, v99
	v_lshlrev_b32_e32 v204, 16, v100
	v_and_b32_e32 v205, 0xffff0000, v100
	v_lshlrev_b32_e32 v206, 16, v101
	v_and_b32_e32 v207, 0xffff0000, v101
	v_lshlrev_b32_e32 v210, 16, v102
	v_and_b32_e32 v211, 0xffff0000, v102
	v_lshlrev_b32_e32 v212, 16, v103
	v_and_b32_e32 v213, 0xffff0000, v103
	v_lshlrev_b32_e32 v214, 16, v104
	v_and_b32_e32 v215, 0xffff0000, v104
	v_lshlrev_b32_e32 v216, 16, v105
	v_and_b32_e32 v217, 0xffff0000, v105
	v_lshlrev_b32_e32 v218, 16, v106
	v_and_b32_e32 v219, 0xffff0000, v106
	v_lshlrev_b32_e32 v220, 16, v107
	v_and_b32_e32 v221, 0xffff0000, v107
	v_mul_f32_e32 v222, v188, v188
	v_mul_f32_e32 v223, v189, v189
	v_mul_f32_e32 v224, v190, v190
	v_mul_f32_e32 v225, v191, v191
	v_fmac_f32_e32 v222, v192, v192
	v_fmac_f32_e32 v223, v193, v193
	v_fmac_f32_e32 v224, v194, v194
	v_fmac_f32_e32 v225, v195, v195
	v_fmac_f32_e32 v222, v196, v196
	v_fmac_f32_e32 v223, v197, v197
	v_fmac_f32_e32 v224, v198, v198
	v_fmac_f32_e32 v225, v199, v199
	v_fmac_f32_e32 v222, v200, v200
	v_fmac_f32_e32 v223, v201, v201
	v_fmac_f32_e32 v224, v202, v202
	v_fmac_f32_e32 v225, v203, v203
	v_fmac_f32_e32 v222, v204, v204
	v_fmac_f32_e32 v223, v205, v205
	v_fmac_f32_e32 v224, v206, v206
	v_fmac_f32_e32 v225, v207, v207
	v_fmac_f32_e32 v222, v210, v210
	v_fmac_f32_e32 v223, v211, v211
	v_fmac_f32_e32 v224, v212, v212
	v_fmac_f32_e32 v225, v213, v213
	v_fmac_f32_e32 v222, v214, v214
	v_fmac_f32_e32 v223, v215, v215
	v_fmac_f32_e32 v224, v216, v216
	v_fmac_f32_e32 v225, v217, v217
	v_fmac_f32_e32 v222, v218, v218
	v_fmac_f32_e32 v223, v219, v219
	v_fmac_f32_e32 v224, v220, v220
	v_fmac_f32_e32 v225, v221, v221
	v_add_f32_e32 v222, v222, v223
	v_add_f32_e32 v224, v224, v225
	v_add_f32_e32 v222, v222, v224
	ds_bpermute_b32 v226, v5, v222
	s_waitcnt lgkmcnt(0)
	v_add_f32_e32 v222, v222, v226
	ds_bpermute_b32 v226, v6, v222
	s_waitcnt lgkmcnt(0)
	v_add_f32_e32 v222, v222, v226
	ds_bpermute_b32 v226, v7, v222
	s_waitcnt lgkmcnt(0)
	v_add_f32_e32 v222, v222, v226
	ds_bpermute_b32 v226, v8, v222
	s_waitcnt lgkmcnt(0)
	v_add_f32_e32 v222, v222, v226
	ds_bpermute_b32 v226, v9, v222
	s_waitcnt lgkmcnt(0)
	v_add_f32_e32 v222, v222, v226
	ds_bpermute_b32 v226, v10, v222
	s_waitcnt lgkmcnt(0)
	v_add_f32_e32 v222, v222, v226
	v_fmamk_f32 v222, v222, 0x3a000000, v11
	v_rsq_f32_e32 v227, v222
	s_nop 0
	v_mul_f32_e32 v188, v188, v227
	v_fmac_f32_e32 v108, v188, v12
	v_mul_f32_e32 v189, v189, v227
	v_fmac_f32_e32 v109, v189, v13
	v_mul_f32_e32 v190, v190, v227
	v_fmac_f32_e32 v110, v190, v14
	v_mul_f32_e32 v191, v191, v227
	v_fmac_f32_e32 v111, v191, v15
	v_mul_f32_e32 v192, v192, v227
	v_fmac_f32_e32 v112, v192, v16
	v_mul_f32_e32 v193, v193, v227
	v_fmac_f32_e32 v113, v193, v17
	v_mul_f32_e32 v194, v194, v227
	v_fmac_f32_e32 v114, v194, v18
	v_mul_f32_e32 v195, v195, v227
	v_fmac_f32_e32 v115, v195, v19
	v_mul_f32_e32 v196, v196, v227
	v_fmac_f32_e32 v116, v196, v20
	v_mul_f32_e32 v197, v197, v227
	v_fmac_f32_e32 v117, v197, v21
	v_mul_f32_e32 v198, v198, v227
	v_fmac_f32_e32 v118, v198, v22
	v_mul_f32_e32 v199, v199, v227
	v_fmac_f32_e32 v119, v199, v23
	v_mul_f32_e32 v200, v200, v227
	v_fmac_f32_e32 v120, v200, v24
	v_mul_f32_e32 v201, v201, v227
	v_fmac_f32_e32 v121, v201, v25
	v_mul_f32_e32 v202, v202, v227
	v_fmac_f32_e32 v122, v202, v26
	v_mul_f32_e32 v203, v203, v227
	v_fmac_f32_e32 v123, v203, v27
	v_mul_f32_e32 v204, v204, v227
	v_fmac_f32_e32 v124, v204, v28
	v_mul_f32_e32 v205, v205, v227
	v_fmac_f32_e32 v125, v205, v29
	v_mul_f32_e32 v206, v206, v227
	v_fmac_f32_e32 v126, v206, v30
	v_mul_f32_e32 v207, v207, v227
	v_fmac_f32_e32 v127, v207, v31
	v_mul_f32_e32 v210, v210, v227
	v_fmac_f32_e32 v128, v210, v32
	v_mul_f32_e32 v211, v211, v227
	v_fmac_f32_e32 v129, v211, v33
	v_mul_f32_e32 v212, v212, v227
	v_fmac_f32_e32 v130, v212, v34
	v_mul_f32_e32 v213, v213, v227
	v_fmac_f32_e32 v131, v213, v35
	v_mul_f32_e32 v214, v214, v227
	v_fmac_f32_e32 v132, v214, v36
	v_mul_f32_e32 v215, v215, v227
	v_fmac_f32_e32 v133, v215, v37
	v_mul_f32_e32 v216, v216, v227
	v_fmac_f32_e32 v134, v216, v38
	v_mul_f32_e32 v217, v217, v227
	v_fmac_f32_e32 v135, v217, v39
	v_mul_f32_e32 v218, v218, v227
	v_fmac_f32_e32 v136, v218, v40
	v_mul_f32_e32 v219, v219, v227
	v_fmac_f32_e32 v137, v219, v41
	v_mul_f32_e32 v220, v220, v227
	v_fmac_f32_e32 v138, v220, v42
	v_mul_f32_e32 v221, v221, v227
	v_fmac_f32_e32 v139, v221, v43
	s_lshl_b32 s4, s2, 13
	s_add_u32 s14, s22, s4
	s_addc_u32 s15, s23, 0
	global_store_dwordx4 v1, v[108:111], s[14:15]
	global_store_dwordx4 v1, v[112:115], s[14:15] offset:16
	global_store_dwordx4 v1, v[116:119], s[14:15] offset:2048
	global_store_dwordx4 v1, v[120:123], s[14:15] offset:2064
	global_store_dwordx4 v2, v[124:127], s[14:15]
	global_store_dwordx4 v2, v[128:131], s[14:15] offset:16
	global_store_dwordx4 v2, v[132:135], s[14:15] offset:2048
	global_store_dwordx4 v2, v[136:139], s[14:15] offset:2064
	s_mov_b32 s2, s30
	s_cmp_ge_u32 s2, 0x2080
	s_cbranch_scc1 .Lp10_done
	s_branch .Lp10_l0
